# attention loops: removed compiler over-drain vmcnt ladders (conditional full drain only on last iteration); MLA loop 4-deep K fragment ring + 16x16x32 row-sum
# baseline (speedup 1.0000x reference)
; __device__ __forceinline__ int crow(int r, int hi) { return (r & 3) + 8 * (r >> 2) + 4 * hi; }
; #define SWRITE(b, i) do { *(bf16x8*)(V_lds + (b) * SHM_V + vst0) = st_[i].vs; *(bf16x8*)(K_lds + (b) * SHM_K + kst0) = st_[i].ks; \
;     if (DQ == 96) { if (tid < 256) *(bf16x8*)(K_lds + (b) * SHM_K + kst2) = st_[i].kr; } } while (0)
; #define SWAIT() do { if (DQ == 96) asm volatile("s_waitcnt vmcnt(3)" ::: "memory"); else asm volatile("s_waitcnt vmcnt(2)" ::: "memory"); } while (0)
; #define SWRITE(b, i) do { *(bf16x8*)(V_lds + (b) * SHM_V + vst0) = st_[i].vs; *(bf16x8*)(K_lds + (b) * SHM_K + kst0) = st_[i].ks; \
;     if (DQ == 96) { if (tid < 256) *(bf16x8*)(K_lds + (b) * SHM_K + kst2) = st_[i].kr; } } while (0)
; #define SWAIT() do { if (DQ == 96) asm volatile("s_waitcnt vmcnt(3)" ::: "memory"); else asm volatile("s_waitcnt vmcnt(2)" ::: "memory"); } while (0)
; __device__ __forceinline__ void win_mask(f32x16& p0, f32x16& p1, int dlt, int hi) {
; #pragma unroll
;     for (int r = 0; r < 16; ++r) { const int d0 = dlt - crow(r, hi), d1 = d0 - 32;
;         if (d0 > 128 || d0 < -128) p0[r] = -INFINITY;
;         if (d1 > 128 || d1 < -128) p1[r] = -INFINITY; }
; }
; template <int DQ, bool WIN, int LDQ, int LDK> ...
;     ...
;         pv(vb0);
;         __syncthreads(); SWAIT(); SWRITE(0, SE);
;         lsum_upd();
;         if (WIN) win_mask(pB0, pB1, qrow - KBASE(j), hi);
;         exp16(pB0);
.LBB0_421:
	ds_read_b64_tr_b16 v[186:187], v182 offset:0
	ds_read_b64_tr_b16 v[188:189], v182 offset:0x400
	ds_read_b64_tr_b16 v[190:191], v182 offset:0x800
	ds_read_b64_tr_b16 v[192:193], v182 offset:0xc00
	ds_read_b64_tr_b16 v[194:195], v182 offset:0x1000
	ds_read_b64_tr_b16 v[196:197], v182 offset:0x1400
	ds_read_b64_tr_b16 v[198:199], v182 offset:0x1800
	ds_read_b64_tr_b16 v[200:201], v182 offset:0x1c00
	s_waitcnt lgkmcnt(0)
	s_nop 0
	v_mfma_f32_32x32x16_bf16 v[2:17], v[106:109], v[186:189], v[2:17]
	ds_read_b64_tr_b16 v[186:187], v182 offset:0x200
	ds_read_b64_tr_b16 v[188:189], v182 offset:0x600
	v_mfma_f32_32x32x16_bf16 v[2:17], v[110:113], v[190:193], v[2:17]
	ds_read_b64_tr_b16 v[190:191], v182 offset:0xa00
	ds_read_b64_tr_b16 v[192:193], v182 offset:0xe00
	v_mfma_f32_32x32x16_bf16 v[2:17], v[138:141], v[194:197], v[2:17]
	ds_read_b64_tr_b16 v[194:195], v182 offset:0x1200
	ds_read_b64_tr_b16 v[196:197], v182 offset:0x1600
	v_mfma_f32_32x32x16_bf16 v[2:17], v[142:145], v[198:201], v[2:17]
	ds_read_b64_tr_b16 v[198:199], v182 offset:0x1a00
	ds_read_b64_tr_b16 v[200:201], v182 offset:0x1e00
	s_waitcnt lgkmcnt(0)
	s_barrier
	s_waitcnt vmcnt(2)
	s_cmp_eq_u64 s[0:1], 0
	s_cbranch_scc1 .Lw_a0win
	s_waitcnt vmcnt(0)
.Lw_a0win:
	ds_write_b128 v179, v[66:69] offset:8192
	ds_write_b128 v180, v[70:73] offset:25600
	v_mov_b64_e32 v[68:69], s[14:15]
	v_mov_b64_e32 v[66:67], s[12:13]
	v_add_u32_e32 v1, 59, v184
	v_cmp_lt_u32_e32 vcc, s84, v1
	v_mfma_f32_32x32x16_bf16 v[34:49], v[106:109], v[66:69], v[34:49]
	v_add_u32_e32 v1, 27, v184
	v_cndmask_b32_e32 v90, v153, v90, vcc
	v_cmp_lt_u32_e32 vcc, s84, v1
	v_add_u32_e32 v1, 58, v184
	v_add_u32_e32 v70, 48, v184
	v_cndmask_b32_e32 v74, v153, v74, vcc
	v_cmp_lt_u32_e32 vcc, s84, v1
	v_mfma_f32_32x32x16_bf16 v[34:49], v[110:113], v[66:69], v[34:49]
	v_add_u32_e32 v1, 26, v184
	v_cndmask_b32_e32 v91, v153, v91, vcc
	v_cmp_lt_u32_e32 vcc, s84, v1
	v_add_u32_e32 v72, 42, v184
	v_lshl_add_u64 v[148:149], v[148:149], 0, s[18:19]
	v_cndmask_b32_e32 v1, v153, v75, vcc
	v_add_u32_e32 v75, 40, v184
	v_mfma_f32_32x32x16_bf16 v[34:49], v[138:141], v[66:69], v[34:49]
	s_add_i32 s4, s4, 2
	v_lshl_add_u64 v[150:151], v[150:151], 0, s[18:19]
	s_waitcnt lgkmcnt(0)
	s_barrier
	v_mfma_f32_32x32x16_bf16 v[34:49], v[142:145], v[66:69], v[34:49]
	v_add_u32_e32 v66, 57, v184
	v_cmp_lt_u32_e32 vcc, s84, v66
	v_add_u32_e32 v66, 25, v184
	v_add_u32_e32 v68, 50, v184
	v_cndmask_b32_e32 v92, v153, v92, vcc
	v_cmp_lt_u32_e32 vcc, s84, v66
	v_add_u32_e32 v66, 56, v184
	v_mfma_f32_32x32x16_bf16 v[18:33], v[106:109], v[186:189], v[18:33]
	v_cndmask_b32_e32 v76, v153, v76, vcc
	v_cmp_lt_u32_e32 vcc, s84, v66
	v_add_u32_e32 v66, 24, v184
	s_nop 0
	v_cndmask_b32_e32 v93, v153, v93, vcc
	v_cmp_lt_u32_e32 vcc, s84, v66
	v_add_u32_e32 v66, 51, v184
	v_mfma_f32_32x32x16_bf16 v[18:33], v[110:113], v[190:193], v[18:33]
	v_cndmask_b32_e32 v67, v153, v77, vcc
	v_cmp_lt_u32_e32 vcc, s84, v66
	v_add_u32_e32 v66, 19, v184
	v_add_u32_e32 v77, 35, v184
	v_cndmask_b32_e32 v94, v153, v94, vcc
	v_cmp_lt_u32_e32 vcc, s84, v66
	v_mfma_f32_32x32x16_bf16 v[18:33], v[138:141], v[194:197], v[18:33]
	s_nop 0
	v_cndmask_b32_e32 v66, v153, v78, vcc
	v_cmp_lt_u32_e32 vcc, s84, v68
	v_add_u32_e32 v68, 18, v184
	v_exp_f32_e32 v138, v90
	v_cndmask_b32_e32 v95, v153, v95, vcc
	v_cmp_lt_u32_e32 vcc, s84, v68
	v_add_u32_e32 v68, 49, v184
	v_mfma_f32_32x32x16_bf16 v[18:33], v[142:145], v[198:201], v[18:33]
	v_cndmask_b32_e32 v69, v153, v79, vcc
	v_cmp_lt_u32_e32 vcc, s84, v68
	v_add_u32_e32 v68, 17, v184
	v_add_u32_e32 v79, 33, v184
	v_cndmask_b32_e32 v96, v153, v96, vcc
	v_cmp_lt_u32_e32 vcc, s84, v68
	v_exp_f32_e32 v142, v91
	v_exp_f32_e32 v139, v92
	v_cndmask_b32_e32 v68, v153, v80, vcc
	v_cmp_lt_u32_e32 vcc, s84, v70
	v_add_u32_e32 v70, 16, v184
	v_exp_f32_e32 v143, v93
	v_cndmask_b32_e32 v97, v153, v97, vcc
	v_cmp_lt_u32_e32 vcc, s84, v70
	v_add_u32_e32 v70, 43, v184
	v_exp_f32_e32 v144, v94
	v_cndmask_b32_e32 v71, v153, v81, vcc
	v_cmp_lt_u32_e32 vcc, s84, v70
	v_add_u32_e32 v70, 11, v184
	v_exp_f32_e32 v186, v95
	v_cndmask_b32_e32 v81, v153, v98, vcc
	v_cmp_lt_u32_e32 vcc, s84, v70
	v_exp_f32_e32 v187, v96
	v_exp_f32_e32 v190, v97
	v_cndmask_b32_e32 v70, v153, v82, vcc
	v_cmp_lt_u32_e32 vcc, s84, v72
	v_add_u32_e32 v72, 10, v184
	v_exp_f32_e32 v81, v81
	v_cndmask_b32_e32 v82, v153, v99, vcc
	v_cmp_lt_u32_e32 vcc, s84, v72
	v_add_u32_e32 v72, 41, v184
	v_exp_f32_e32 v140, v82
	v_cndmask_b32_e32 v73, v153, v83, vcc
	v_cmp_lt_u32_e32 vcc, s84, v72
	v_add_u32_e32 v72, 9, v184
	s_nop 0
	v_cndmask_b32_e32 v83, v153, v100, vcc
	v_cmp_lt_u32_e32 vcc, s84, v72
	v_exp_f32_e32 v141, v83
	s_nop 0
	v_cndmask_b32_e32 v72, v153, v84, vcc
	v_cmp_lt_u32_e32 vcc, s84, v75
	v_add_u32_e32 v75, 8, v184
	s_nop 0
	v_cndmask_b32_e32 v84, v153, v101, vcc
	v_cmp_lt_u32_e32 vcc, s84, v75
	v_exp_f32_e32 v145, v84
	s_nop 0
	v_cndmask_b32_e32 v75, v153, v85, vcc
	v_cmp_lt_u32_e32 vcc, s84, v77
	v_add_u32_e32 v77, 3, v184
	s_nop 0
	v_cndmask_b32_e32 v85, v153, v102, vcc
	v_cmp_lt_u32_e32 vcc, s84, v77
	v_add_u32_e32 v77, 34, v184
	v_exp_f32_e32 v185, v85
	v_cndmask_b32_e32 v78, v153, v86, vcc
	v_cmp_lt_u32_e32 vcc, s84, v77
	v_add_u32_e32 v77, 2, v184
	s_nop 0
	v_cndmask_b32_e32 v86, v153, v103, vcc
	v_cmp_lt_u32_e32 vcc, s84, v77
	v_exp_f32_e32 v188, v86
	s_nop 0
	v_cndmask_b32_e32 v77, v153, v87, vcc
	v_cmp_lt_u32_e32 vcc, s84, v79
	v_add_u32_e32 v79, 1, v184
	s_nop 0
	v_cndmask_b32_e32 v87, v153, v104, vcc
	v_cmp_lt_u32_e32 vcc, s84, v79
	v_add_u32_e32 v79, 32, v184
	v_exp_f32_e32 v189, v87
	v_cndmask_b32_e32 v80, v153, v88, vcc
	v_cmp_lt_u32_e32 vcc, s84, v79
	s_nop 1
	v_cndmask_b32_e32 v88, v153, v105, vcc
	v_exp_f32_e32 v191, v88
	v_cmp_lt_u32_e32 vcc, s84, v184
	v_add_u32_e32 v184, 0xffffff80, v184
	s_nop 0
	v_cndmask_b32_e32 v79, v153, v89, vcc
	s_and_b64 vcc, exec, s[0:1]
	s_cbranch_vccnz .LBB0_426

; #define SWRITE(b, i) do { *(bf16x8*)(V_lds + (b) * SHM_V + vst0) = st_[i].vs; *(bf16x8*)(K_lds + (b) * SHM_K + kst0) = st_[i].ks; \
;     if (DQ == 96) { if (tid < 256) *(bf16x8*)(K_lds + (b) * SHM_K + kst2) = st_[i].kr; } } while (0)
; #define SWAIT() do { if (DQ == 96) asm volatile("s_waitcnt vmcnt(3)" ::: "memory"); else asm volatile("s_waitcnt vmcnt(2)" ::: "memory"); } while (0)
; #define SWRITE(b, i) do { *(bf16x8*)(V_lds + (b) * SHM_V + vst0) = st_[i].vs; *(bf16x8*)(K_lds + (b) * SHM_K + kst0) = st_[i].ks; \
;     if (DQ == 96) { if (tid < 256) *(bf16x8*)(K_lds + (b) * SHM_K + kst2) = st_[i].kr; } } while (0)
; #define SWAIT() do { if (DQ == 96) asm volatile("s_waitcnt vmcnt(3)" ::: "memory"); else asm volatile("s_waitcnt vmcnt(2)" ::: "memory"); } while (0)
; template <int DQ, bool WIN, int LDQ, int LDK> ...
;     ...
;         pv(vb0);
;         __syncthreads(); SWAIT(); SWRITE(0, SE);
;         lsum_upd();
;         if (WIN) win_mask(pB0, pB1, qrow - KBASE(j), hi);
;         exp16(pB0);
.LBB0_492:
	ds_read_b64_tr_b16 v[160:161], v155 offset:0
	ds_read_b64_tr_b16 v[162:163], v155 offset:0x400
	ds_read_b64_tr_b16 v[164:165], v155 offset:0x800
	ds_read_b64_tr_b16 v[166:167], v155 offset:0xc00
	ds_read_b64_tr_b16 v[168:169], v155 offset:0x1000
	ds_read_b64_tr_b16 v[170:171], v155 offset:0x1400
	ds_read_b64_tr_b16 v[172:173], v155 offset:0x1800
	ds_read_b64_tr_b16 v[174:175], v155 offset:0x1c00
	s_waitcnt lgkmcnt(0)
	s_nop 0
	v_mfma_f32_32x32x16_bf16 v[2:17], v[94:97], v[160:163], v[2:17]
	ds_read_b64_tr_b16 v[160:161], v155 offset:0x200
	ds_read_b64_tr_b16 v[162:163], v155 offset:0x600
	v_mfma_f32_32x32x16_bf16 v[2:17], v[90:93], v[164:167], v[2:17]
	ds_read_b64_tr_b16 v[164:165], v155 offset:0xa00
	ds_read_b64_tr_b16 v[166:167], v155 offset:0xe00
	v_mfma_f32_32x32x16_bf16 v[2:17], v[86:89], v[168:171], v[2:17]
	ds_read_b64_tr_b16 v[168:169], v155 offset:0x1200
	ds_read_b64_tr_b16 v[170:171], v155 offset:0x1600
	ds_read_b64_tr_b16 v[176:177], v155 offset:0x1a00
	ds_read_b64_tr_b16 v[178:179], v155 offset:0x1e00
	s_waitcnt lgkmcnt(0)
	v_mfma_f32_32x32x16_bf16 v[2:17], v[82:85], v[172:175], v[2:17]
	v_mfma_f32_32x32x16_bf16 v[18:33], v[94:97], v[160:163], v[18:33]
	s_barrier
	s_waitcnt vmcnt(2)
	s_cmp_eq_u64 s[0:1], 0
	s_cbranch_scc1 .Lw_a0dense
	s_waitcnt vmcnt(0)
.Lw_a0dense:
	ds_write_b128 v158, v[138:141] offset:8192
	ds_write_b128 v157, v[142:145] offset:25600
	v_exp_f32_e32 v138, v98
	v_exp_f32_e32 v139, v99
	v_mfma_f32_32x32x16_bf16 v[18:33], v[90:93], v[164:167], v[18:33]
	v_exp_f32_e32 v162, v100
	v_exp_f32_e32 v165, v101
	v_exp_f32_e32 v163, v102
	v_exp_f32_e32 v166, v103
	v_exp_f32_e32 v164, v104
	v_exp_f32_e32 v167, v105
	v_exp_f32_e32 v140, v106
	v_mfma_f32_32x32x16_bf16 v[18:33], v[86:89], v[168:171], v[18:33]
	v_mov_b64_e32 v[170:171], s[14:15]
	v_mov_b64_e32 v[168:169], s[12:13]
	v_exp_f32_e32 v144, v107
	v_exp_f32_e32 v141, v108
	v_exp_f32_e32 v145, v109
	v_exp_f32_e32 v142, v110
	v_exp_f32_e32 v160, v111
	v_mfma_f32_32x32x16_bf16 v[34:49], v[94:97], v[168:171], v[34:49]
	v_exp_f32_e32 v143, v112
	v_exp_f32_e32 v161, v113
	v_lshl_add_u64 v[148:149], v[148:149], 0, s[18:19]
	s_and_b64 vcc, exec, s[0:1]
	s_waitcnt lgkmcnt(0)
	s_barrier
	v_mfma_f32_32x32x16_bf16 v[34:49], v[90:93], v[168:171], v[34:49]
	v_mfma_f32_32x32x16_bf16 v[34:49], v[86:89], v[168:171], v[34:49]
	v_mfma_f32_32x32x16_bf16 v[18:33], v[82:85], v[176:179], v[18:33]
	v_mfma_f32_32x32x16_bf16 v[34:49], v[82:85], v[168:171], v[34:49]
	s_cbranch_vccnz .LBB0_495

; #define SBAR() __builtin_amdgcn_sched_barrier(0)
; #define SLOAD(i, k0) do { st_[i].vs = *reinterpret_cast<const bf16x8*>(&Vh[(size_t)((k0) + sr) * LDK + sc]); \
;     st_[i].ks = *reinterpret_cast<const bf16x8*>(&Kh[(size_t)((k0) + sr) * LDK + sc]); \
;     if (DQ == 96) st_[i].kr = *reinterpret_cast<const bf16x8*>(&Kr[(size_t)((k0) + sr2) * 32 + sc2]); } while (0)
; #define SLOAD(i, k0) do { st_[i].vs = *reinterpret_cast<const bf16x8*>(&Vh[(size_t)((k0) + sr) * LDK + sc]); \
;     st_[i].ks = *reinterpret_cast<const bf16x8*>(&Kh[(size_t)((k0) + sr) * LDK + sc]); \
;     if (DQ == 96) st_[i].kr = *reinterpret_cast<const bf16x8*>(&Kr[(size_t)((k0) + sr2) * 32 + sc2]); } while (0)
; template <int DQ>
; __device__ __forceinline__ void qkt(f32x16& p0, f32x16& p1, const char* Ks, const bf16x8* qr, const f32x16& ci, int r32, int hi) {
;     constexpr int KROW = ACfg<DQ>::KROW;
; #pragma unroll
;     for (int d0 = 0; d0 < ACfg<DQ>::ND; ++d0) { const int cb = (d0 * 16 + hi * 8) * 2;
;         bf16x8 b0 = *reinterpret_cast<const bf16x8*>(Ks + r32 * KROW + cb);
;         bf16x8 b1 = *reinterpret_cast<const bf16x8*>(Ks + (32 + r32) * KROW + cb);
;         p0 = __builtin_amdgcn_mfma_f32_32x32x16_bf16(b0, qr[d0], d0 == 0 ? ci : p0, 0, 0, 0);
;         p1 = __builtin_amdgcn_mfma_f32_32x32x16_bf16(b1, qr[d0], d0 == 0 ? ci : p1, 0, 0, 0); }
; }
; template <int DQ, bool WIN, int LDQ, int LDK> ...
;     ...
;         SBAR(); qkt<DQ>(pA0, pA1, K_lds, qr, minit, r32, hi);
;         finish(pB0, pB1); SBAR();
;         if (j + 3 < NT) SLOAD(SE, KBASE(j + 3)); SBAR();
;         pv(vb0 + SHM_V);
.LBB0_1093:
	s_or_b64 exec, exec, s[18:19]
	v_exp_f32_e32 v161, v96
	v_exp_f32_e32 v196, v97
	v_mfma_f32_16x16x32_bf16 v[32:35], v[80:83], v[36:39], v[32:35]
	v_exp_f32_e32 v158, v98
	v_exp_f32_e32 v168, v99
	v_exp_f32_e32 v159, v100
	v_exp_f32_e32 v169, v101
	v_exp_f32_e32 v160, v102
	v_exp_f32_e32 v195, v103
	v_exp_f32_e32 v154, v105
	v_mfma_f32_16x16x32_bf16 v[32:35], v[84:87], v[36:39], v[32:35]
	v_exp_f32_e32 v155, v107
	v_exp_f32_e32 v156, v109
	v_exp_f32_e32 v157, v111
	s_mov_b64 s[34:35], 0x2000
	s_mov_b64 s[18:19], 0x80000
	v_lshl_add_u64 v[162:163], v[162:163], 0, s[34:35]
	v_lshl_add_u64 v[164:165], v[164:165], 0, s[18:19]
	v_mfma_f32_16x16x32_bf16 v[32:35], v[88:91], v[36:39], v[32:35]
	v_lshl_add_u64 v[166:167], v[166:167], 0, s[34:35]
	s_and_b64 vcc, exec, s[4:5]
	s_waitcnt lgkmcnt(0)
	s_barrier
	v_mfma_f32_16x16x32_bf16 v[32:35], v[92:95], v[36:39], v[32:35]
	v_exp_f32_e32 v150, v104
	v_exp_f32_e32 v151, v106
	v_exp_f32_e32 v152, v108
	v_exp_f32_e32 v153, v110
	s_cbranch_vccnz .LBB0_1100
.LBB0_1094:
	ds_read_b128 v[80:83], v191 offset:29696
	ds_read_b128 v[40:43], v191 offset:36352
	ds_read_b128 v[44:47], v191 offset:29728
	ds_read_b128 v[210:213], v191 offset:36384
	ds_read_b128 v[214:217], v191 offset:29760
	v_exp_f32_e32 v72, v72
	v_exp_f32_e32 v73, v73
	v_exp_f32_e32 v74, v74
	s_waitcnt lgkmcnt(4)
	v_mfma_f32_32x32x16_bf16 v[96:111], v[80:83], v[134:137], v[48:63]
	v_exp_f32_e32 v75, v75
	v_exp_f32_e32 v197, v64
	v_exp_f32_e32 v206, v77
	v_exp_f32_e32 v207, v78
	v_exp_f32_e32 v208, v79
	s_waitcnt lgkmcnt(3)
	v_mfma_f32_32x32x16_bf16 v[80:95], v[40:43], v[134:137], v[48:63]
	ds_read_b128 v[40:43], v191 offset:36416
	s_waitcnt lgkmcnt(3)
	v_mfma_f32_32x32x16_bf16 v[96:111], v[44:47], v[130:133], v[96:111]
	ds_read_b128 v[44:47], v191 offset:29792
	s_waitcnt lgkmcnt(3)
	v_mfma_f32_32x32x16_bf16 v[80:95], v[210:213], v[130:133], v[80:95]
	ds_read_b128 v[210:213], v191 offset:36448
	s_waitcnt lgkmcnt(3)
	v_mfma_f32_32x32x16_bf16 v[96:111], v[214:217], v[126:129], v[96:111]
	ds_read_b128 v[214:217], v191 offset:29824
	s_waitcnt lgkmcnt(3)
	v_mfma_f32_32x32x16_bf16 v[80:95], v[40:43], v[126:129], v[80:95]
	ds_read_b128 v[40:43], v191 offset:36480
	s_waitcnt lgkmcnt(3)
	v_mfma_f32_32x32x16_bf16 v[96:111], v[44:47], v[122:125], v[96:111]
	ds_read_b128 v[44:47], v191 offset:29856
	s_waitcnt lgkmcnt(3)
	v_mfma_f32_32x32x16_bf16 v[80:95], v[210:213], v[122:125], v[80:95]
	ds_read_b128 v[210:213], v191 offset:36512
	s_waitcnt lgkmcnt(3)
	v_mfma_f32_32x32x16_bf16 v[96:111], v[214:217], v[118:121], v[96:111]
	s_waitcnt lgkmcnt(2)
	v_mfma_f32_32x32x16_bf16 v[80:95], v[40:43], v[118:121], v[80:95]
	s_waitcnt lgkmcnt(1)
	v_mfma_f32_32x32x16_bf16 v[96:111], v[44:47], v[114:117], v[96:111]
	v_exp_f32_e32 v198, v65
	v_exp_f32_e32 v199, v66
	v_exp_f32_e32 v200, v67
	v_exp_f32_e32 v201, v68
	v_cvt_pk_bf16_f32 v68, v161, v196
	s_waitcnt lgkmcnt(0)
	v_mfma_f32_32x32x16_bf16 v[80:95], v[210:213], v[114:117], v[80:95]
	v_exp_f32_e32 v202, v69
	v_exp_f32_e32 v203, v70
	v_exp_f32_e32 v204, v71
	v_exp_f32_e32 v205, v76
	v_cvt_pk_bf16_f32 v69, v158, v168
	v_cvt_pk_bf16_f32 v70, v159, v169
	v_cvt_pk_bf16_f32 v71, v160, v195
	v_cvt_pk_bf16_f32 v64, v150, v154
	v_cvt_pk_bf16_f32 v65, v151, v155
	v_cvt_pk_bf16_f32 v66, v152, v156
	v_cvt_pk_bf16_f32 v67, v153, v157
	v_cvt_pk_bf16_f32 v76, v197, v198
	v_cvt_pk_bf16_f32 v77, v199, v200
	v_cvt_pk_bf16_f32 v78, v201, v202
	v_cvt_pk_bf16_f32 v79, v203, v204
	v_cvt_pk_bf16_f32 v72, v72, v73
	v_cvt_pk_bf16_f32 v73, v74, v75
	v_cvt_pk_bf16_f32 v74, v205, v206
	v_cvt_pk_bf16_f32 v75, v207, v208
	v_lshl_add_u64 v[168:169], s[26:27], 0, v[164:165]
	s_mov_b32 s4, 0x218c0000
	v_add_co_u32_e32 v150, vcc, s4, v168
	s_nop 1
	v_addc_co_u32_e32 v151, vcc, 0, v169, vcc
	global_load_dwordx4 v[154:157], v[150:151], off offset:128
	global_load_dwordx4 v[158:161], v[150:151], off
	v_lshl_add_u64 v[150:151], s[26:27], 0, v[166:167]
	global_load_dwordx4 v[150:153], v[150:151], off
	ds_read_b64_tr_b16 v[196:197], v194 offset:0
	ds_read_b64_tr_b16 v[198:199], v194 offset:0x400
	ds_read_b64_tr_b16 v[200:201], v194 offset:0x800
	ds_read_b64_tr_b16 v[202:203], v194 offset:0xc00
	ds_read_b64_tr_b16 v[204:205], v194 offset:0x1000
	ds_read_b64_tr_b16 v[206:207], v194 offset:0x1400
	ds_read_b64_tr_b16 v[208:209], v194 offset:0x1800
	ds_read_b64_tr_b16 v[210:211], v194 offset:0x1c00
	s_waitcnt lgkmcnt(0)
	s_nop 0
	v_mfma_f32_32x32x16_bf16 v[0:15], v[68:71], v[196:199], v[0:15]
	ds_read_b64_tr_b16 v[196:197], v194 offset:0x200
	ds_read_b64_tr_b16 v[198:199], v194 offset:0x600
	v_mfma_f32_32x32x16_bf16 v[0:15], v[64:67], v[200:203], v[0:15]
	ds_read_b64_tr_b16 v[200:201], v194 offset:0xa00
	ds_read_b64_tr_b16 v[202:203], v194 offset:0xe00
	v_mfma_f32_32x32x16_bf16 v[0:15], v[76:79], v[204:207], v[0:15]
	ds_read_b64_tr_b16 v[204:205], v194 offset:0x1200
	ds_read_b64_tr_b16 v[206:207], v194 offset:0x1600
	v_mfma_f32_32x32x16_bf16 v[0:15], v[72:75], v[208:211], v[0:15]
	ds_read_b64_tr_b16 v[208:209], v194 offset:0x1a00
	ds_read_b64_tr_b16 v[210:211], v194 offset:0x1e00
	s_waitcnt lgkmcnt(0)
	v_mfma_f32_32x32x16_bf16 v[16:31], v[68:71], v[196:199], v[16:31]
	s_barrier
	s_waitcnt vmcnt(3)
	s_waitcnt vmcnt(5)
	ds_write_b128 v192, v[138:141]
	s_waitcnt vmcnt(4)
	ds_write_b128 v193, v[142:145] offset:16384
	v_mfma_f32_32x32x16_bf16 v[16:31], v[64:67], v[200:203], v[16:31]
	v_mfma_f32_32x32x16_bf16 v[16:31], v[76:79], v[204:207], v[16:31]
	v_mfma_f32_32x32x16_bf16 v[16:31], v[72:75], v[208:211], v[16:31]
	s_and_saveexec_b64 s[4:5], s[40:41]
	s_cbranch_execz .LBB0_1096
	s_waitcnt vmcnt(3)
	ds_write_b128 v112, v[146:149] offset:16512
; #define SBAR() __builtin_amdgcn_sched_barrier(0)
; #define SLOAD(i, k0) do { st_[i].vs = *reinterpret_cast<const bf16x8*>(&Vh[(size_t)((k0) + sr) * LDK + sc]); \
;     st_[i].ks = *reinterpret_cast<const bf16x8*>(&Kh[(size_t)((k0) + sr) * LDK + sc]); \
;     if (DQ == 96) st_[i].kr = *reinterpret_cast<const bf16x8*>(&Kr[(size_t)((k0) + sr2) * 32 + sc2]); } while (0)
; #define SWRITE(b, i) do { *(bf16x8*)(V_lds + (b) * SHM_V + vst0) = st_[i].vs; *(bf16x8*)(K_lds + (b) * SHM_K + kst0) = st_[i].ks; \
;     if (DQ == 96) { if (tid < 256) *(bf16x8*)(K_lds + (b) * SHM_K + kst2) = st_[i].kr; } } while (0)
; #define SWAIT() do { if (DQ == 96) asm volatile("s_waitcnt vmcnt(3)" ::: "memory"); else asm volatile("s_waitcnt vmcnt(2)" ::: "memory"); } while (0)
; #define SLOAD(i, k0) do { st_[i].vs = *reinterpret_cast<const bf16x8*>(&Vh[(size_t)((k0) + sr) * LDK + sc]); \
;     st_[i].ks = *reinterpret_cast<const bf16x8*>(&Kh[(size_t)((k0) + sr) * LDK + sc]); \
;     if (DQ == 96) st_[i].kr = *reinterpret_cast<const bf16x8*>(&Kr[(size_t)((k0) + sr2) * 32 + sc2]); } while (0)
; template <int DQ>
; __device__ __forceinline__ void qkt(f32x16& p0, f32x16& p1, const char* Ks, const bf16x8* qr, const f32x16& ci, int r32, int hi) {
;     constexpr int KROW = ACfg<DQ>::KROW;
; #pragma unroll
;     for (int d0 = 0; d0 < ACfg<DQ>::ND; ++d0) { const int cb = (d0 * 16 + hi * 8) * 2;
;         bf16x8 b0 = *reinterpret_cast<const bf16x8*>(Ks + r32 * KROW + cb);
;         bf16x8 b1 = *reinterpret_cast<const bf16x8*>(Ks + (32 + r32) * KROW + cb);
;         p0 = __builtin_amdgcn_mfma_f32_32x32x16_bf16(b0, qr[d0], d0 == 0 ? ci : p0, 0, 0, 0);
;         p1 = __builtin_amdgcn_mfma_f32_32x32x16_bf16(b1, qr[d0], d0 == 0 ? ci : p1, 0, 0, 0); }
; }
; template <int DQ, bool WIN, int LDQ, int LDK> ...
;     ...
;         lsum_upd();
;         if (WIN) win_mask(pB0, pB1, qrow - KBASE(j), hi);
;         exp16(pB0);
;         __syncthreads();
;         SBAR(); qkt<DQ>(pA0, pA1, K_lds, qr, minit, r32, hi);
;         finish(pB0, pB1); SBAR();
;         if (j + 3 < NT) SLOAD(SE, KBASE(j + 3)); SBAR();
;         pv(vb0 + SHM_V);
;         __syncthreads(); SWAIT(); SWRITE(1, SO);
;         lsum_upd();
;         if (WIN) win_mask(pA0, pA1, qrow - KBASE(j + 1), hi);
;         exp16(pA0);
;         __syncthreads();
;     }
.LBB0_1096:
	s_or_b64 exec, exec, s[4:5]
	s_add_i32 s17, s17, 2
	v_exp_f32_e32 v195, v96
	v_mfma_f32_16x16x32_bf16 v[32:35], v[68:71], v[36:39], v[32:35]
	v_exp_f32_e32 v204, v97
	v_exp_f32_e32 v205, v98
	v_exp_f32_e32 v206, v99
	v_exp_f32_e32 v207, v100
	v_exp_f32_e32 v208, v101
	v_exp_f32_e32 v209, v102
	v_exp_f32_e32 v210, v103
	v_mfma_f32_16x16x32_bf16 v[32:35], v[64:67], v[36:39], v[32:35]
	v_exp_f32_e32 v211, v104
	v_exp_f32_e32 v212, v105
	v_exp_f32_e32 v213, v106
	v_exp_f32_e32 v214, v107
	v_exp_f32_e32 v215, v108
	v_exp_f32_e32 v216, v109
	v_exp_f32_e32 v217, v110
	v_mfma_f32_16x16x32_bf16 v[32:35], v[76:79], v[36:39], v[32:35]
	v_exp_f32_e32 v218, v111
	s_waitcnt lgkmcnt(0)
	s_barrier
	v_mfma_f32_16x16x32_bf16 v[32:35], v[72:75], v[36:39], v[32:35]
	ds_read_b128 v[64:67], v191 offset:16384
	ds_read_b128 v[40:43], v191 offset:23040
	ds_read_b128 v[44:47], v191 offset:16416
	ds_read_b128 v[138:141], v191 offset:23072
	ds_read_b128 v[142:145], v191 offset:16448
	v_exp_f32_e32 v95, v95
	v_exp_f32_e32 v219, v88
	v_exp_f32_e32 v220, v89
	s_waitcnt lgkmcnt(4)
	v_mfma_f32_32x32x16_bf16 v[96:111], v[64:67], v[134:137], v[48:63]
	v_exp_f32_e32 v221, v90
	v_exp_f32_e32 v222, v91
	v_exp_f32_e32 v223, v92
	v_exp_f32_e32 v224, v93
	v_exp_f32_e32 v225, v94
	s_waitcnt lgkmcnt(3)
	v_mfma_f32_32x32x16_bf16 v[64:79], v[40:43], v[134:137], v[48:63]
	ds_read_b128 v[40:43], v191 offset:23104
	s_waitcnt lgkmcnt(3)
	v_mfma_f32_32x32x16_bf16 v[96:111], v[44:47], v[130:133], v[96:111]
	ds_read_b128 v[44:47], v191 offset:16480
	s_waitcnt lgkmcnt(3)
	v_mfma_f32_32x32x16_bf16 v[64:79], v[138:141], v[130:133], v[64:79]
	ds_read_b128 v[138:141], v191 offset:23136
	s_waitcnt lgkmcnt(3)
	v_mfma_f32_32x32x16_bf16 v[96:111], v[142:145], v[126:129], v[96:111]
	ds_read_b128 v[142:145], v191 offset:16512
	s_waitcnt lgkmcnt(3)
	v_mfma_f32_32x32x16_bf16 v[64:79], v[40:43], v[126:129], v[64:79]
	ds_read_b128 v[40:43], v191 offset:23168
	s_waitcnt lgkmcnt(3)
	v_mfma_f32_32x32x16_bf16 v[96:111], v[44:47], v[122:125], v[96:111]
	ds_read_b128 v[44:47], v191 offset:16544
	s_waitcnt lgkmcnt(3)
	v_mfma_f32_32x32x16_bf16 v[64:79], v[138:141], v[122:125], v[64:79]
	ds_read_b128 v[138:141], v191 offset:23200
	s_waitcnt lgkmcnt(3)
	v_mfma_f32_32x32x16_bf16 v[96:111], v[142:145], v[118:121], v[96:111]
	s_waitcnt lgkmcnt(2)
	v_mfma_f32_32x32x16_bf16 v[64:79], v[40:43], v[118:121], v[64:79]
	s_waitcnt lgkmcnt(1)
	v_mfma_f32_32x32x16_bf16 v[96:111], v[44:47], v[114:117], v[96:111]
	v_exp_f32_e32 v196, v80
	v_exp_f32_e32 v197, v81
	v_exp_f32_e32 v198, v82
	v_exp_f32_e32 v199, v83
	v_cvt_pk_bf16_f32 v80, v195, v204
	v_cvt_pk_bf16_f32 v81, v205, v206
	v_cvt_pk_bf16_f32 v82, v207, v208
	s_waitcnt lgkmcnt(0)
	v_mfma_f32_32x32x16_bf16 v[64:79], v[138:141], v[114:117], v[64:79]
	v_exp_f32_e32 v200, v84
	v_exp_f32_e32 v201, v85
	v_exp_f32_e32 v202, v86
	v_exp_f32_e32 v203, v87
	v_cvt_pk_bf16_f32 v83, v209, v210
	v_cvt_pk_bf16_f32 v84, v211, v212
	v_cvt_pk_bf16_f32 v85, v213, v214
	v_cvt_pk_bf16_f32 v86, v215, v216
	v_cvt_pk_bf16_f32 v87, v217, v218
	v_cvt_pk_bf16_f32 v88, v196, v197
	v_cvt_pk_bf16_f32 v89, v198, v199
	v_cvt_pk_bf16_f32 v90, v200, v201
	v_cvt_pk_bf16_f32 v91, v202, v203
	v_cvt_pk_bf16_f32 v92, v219, v220
	v_cvt_pk_bf16_f32 v93, v221, v222
	v_cvt_pk_bf16_f32 v94, v223, v224
	v_cvt_pk_bf16_f32 v95, v225, v95
	s_cmpk_gt_u32 s17, 0x7c
	s_cselect_b64 s[4:5], -1, 0
	s_and_b64 vcc, exec, s[4:5]
	s_cbranch_vccnz .LBB0_1098
	v_add_co_u32_e32 v142, vcc, 0x21900000, v168
	s_waitcnt vmcnt(3)
	v_lshl_add_u64 v[146:147], s[26:27], 0, v[162:163]
	v_addc_co_u32_e32 v143, vcc, 0, v169, vcc
	global_load_dwordx4 v[138:141], v[142:143], off offset:128
	s_nop 0
	global_load_dwordx4 v[142:145], v[142:143], off
	s_nop 0
	global_load_dwordx4 v[146:149], v[146:147], off
.LBB0_1098:
	ds_read_b64_tr_b16 v[196:197], v190 offset:0
	ds_read_b64_tr_b16 v[198:199], v190 offset:0x400
	ds_read_b64_tr_b16 v[200:201], v190 offset:0x800
	ds_read_b64_tr_b16 v[202:203], v190 offset:0xc00
	ds_read_b64_tr_b16 v[204:205], v190 offset:0x1000
	ds_read_b64_tr_b16 v[206:207], v190 offset:0x1400
	ds_read_b64_tr_b16 v[208:209], v190 offset:0x1800
	ds_read_b64_tr_b16 v[210:211], v190 offset:0x1c00
	s_waitcnt lgkmcnt(0)
	s_nop 0
	v_mfma_f32_32x32x16_bf16 v[0:15], v[80:83], v[196:199], v[0:15]
	ds_read_b64_tr_b16 v[196:197], v190 offset:0x200
	ds_read_b64_tr_b16 v[198:199], v190 offset:0x600
	v_mfma_f32_32x32x16_bf16 v[0:15], v[84:87], v[200:203], v[0:15]
	ds_read_b64_tr_b16 v[200:201], v190 offset:0xa00
	ds_read_b64_tr_b16 v[202:203], v190 offset:0xe00
	v_mfma_f32_32x32x16_bf16 v[0:15], v[88:91], v[204:207], v[0:15]
	ds_read_b64_tr_b16 v[204:205], v190 offset:0x1200
	ds_read_b64_tr_b16 v[206:207], v190 offset:0x1600
	v_mfma_f32_32x32x16_bf16 v[0:15], v[92:95], v[208:211], v[0:15]
	ds_read_b64_tr_b16 v[208:209], v190 offset:0x1a00
	ds_read_b64_tr_b16 v[210:211], v190 offset:0x1e00
	s_waitcnt lgkmcnt(0)
	v_mfma_f32_32x32x16_bf16 v[16:31], v[80:83], v[196:199], v[16:31]
	s_barrier
	s_waitcnt vmcnt(3)
	s_cmp_eq_u64 s[4:5], 0
	s_cbranch_scc1 .Lw_mla
	s_waitcnt vmcnt(0)
.Lw_mla:
	ds_write_b128 v192, v[154:157] offset:8192
	ds_write_b128 v193, v[158:161] offset:29696
	v_mfma_f32_32x32x16_bf16 v[16:31], v[84:87], v[200:203], v[16:31]
	v_mfma_f32_32x32x16_bf16 v[16:31], v[88:91], v[204:207], v[16:31]
	v_mfma_f32_32x32x16_bf16 v[16:31], v[92:95], v[208:211], v[16:31]
	s_and_saveexec_b64 s[18:19], s[40:41]
	s_cbranch_execz .LBB0_1093
	ds_write_b128 v112, v[150:153] offset:29824
	s_branch .LBB0_1093
